# v7 + panel_rs_fill issues its 4 rowss loads together (was 4 serial vmcnt0 round trips) + SSM pass-B tile loop waits vmcnt(1) so the y store stays in flight
# baseline (speedup 1.0000x reference)
; #define LAS __attribute__((address_space(3)))
; __device__ __forceinline__ void ssm_mfma(const Params& P, int li, const bf16_t* __restrict__ proj, bf16_t* __restrict__ ybuf, LAS unsigned char* ldsl) {
;     ...
;             for (int tile = 0; tile < 16; ++tile) {
;                 *(LAS u32x4*)(ut + lane * 16) = un;
;                 if (tile < 15) un = *(const u32x4*)(ua + (size_t)(tile + 1) * 16 * 1280);
;                 const u32x4 uc = *(const LAS u32x4*)(ut + (sigA * 16 + rA) * 32 + hi * 16);
.LBB0_256:
	v_mov_b32_e32 v160, v142
	v_mov_b32_e32 v161, v143
	v_mov_b32_e32 v151, v144
	v_mov_b32_e32 v159, v145
	s_and_b64 vcc, exec, s[0:1]
	s_cbranch_vccz .Lssm_w0
	s_waitcnt vmcnt(1)
	s_branch .Lssm_wd

; #define LAS __attribute__((address_space(3)))
; __device__ __forceinline__ void ssm_mfma(const Params& P, int li, const bf16_t* __restrict__ proj, bf16_t* __restrict__ ybuf, LAS unsigned char* ldsl) {
;     ...
;                 *(LAS u32x4*)(ut + lane * 16) = un;
;                 if (tile < 15) un = *(const u32x4*)(ua + (size_t)(tile + 1) * 16 * 1280);
.Lssm_wd:
	s_cmp_eq_u32 s6, 0x3c000
	ds_write_b128 v158, v[104:107]
	s_cbranch_scc1 .LBB0_258
	global_load_dwordx4 v[104:107], v[140:141], off

; #define LAS __attribute__((address_space(3)))
; __device__ __forceinline__ void panel_rs_fill(const float* rowss, int pm, LAS float* rs_lds, int tid) {
;     if (tid < 256) {
;         const float* p = rowss + (size_t)(pm * 256 + tid) * 16; float sacc = 0.f;
; #pragma unroll
;         for (int q = 0; q < 4; ++q) { const f32x4 a = *(const f32x4*)(p + 4 * q); sacc += (a[0] + a[1]) + (a[2] + a[3]); asm volatile("" : "+v"(sacc)); }
;         rs_lds[tid] = __builtin_amdgcn_rsqf(sacc * (1.f / 1024.f) + EPS);
;     }
;     __device__ __forceinline__ void operator()(const f32x4 (&acc)[2][2][4][2], const Unit& u, int wr, int wc, int fr, int fq) const {
;     ...
;         if (((volatile LAS int*)rs_lds)[256] != u.pm) panel_rs_fill(rowss, u.pm, rs_lds, (wr * 4 + wc) * 64 + fq * 16 + fr);
.LBB0_405:
	s_cmp_eq_u32 s93, 1
	s_mov_b64 s[10:11], -1
	s_cbranch_scc1 .LBB0_413
	v_mov_b32_e32 v128, s46
	ds_read_b32 v128, v128 offset:1024
	s_waitcnt lgkmcnt(0)
	v_cmp_eq_u32_e32 vcc, s94, v128
	s_cbranch_vccnz .LBB0_412
	s_mov_b64 s[10:11], exec
	v_readlane_b32 s4, v226, 35
	v_readlane_b32 s5, v226, 36
	s_and_b64 s[4:5], s[10:11], s[4:5]
	s_mov_b64 exec, s[4:5]
	s_cbranch_execz .LBB0_409
	v_add_u32_e32 v128, s40, v201
	v_ashrrev_i32_e32 v129, 31, v128
	v_readlane_b32 s4, v226, 37
	v_lshlrev_b64 v[128:129], 6, v[128:129]
	v_readlane_b32 s5, v226, 38
	s_nop 1
	v_lshl_add_u64 v[132:133], s[4:5], 0, v[128:129]
	global_load_dwordx4 v[128:131], v[132:133], off
	global_load_dwordx4 v[228:231], v[132:133], off offset:16
	global_load_dwordx4 v[232:235], v[132:133], off offset:32
	global_load_dwordx4 v[236:239], v[132:133], off offset:48
	s_waitcnt vmcnt(3)
	v_add_f32_e32 v134, v129, v128
	v_add_f32_e32 v135, v130, v131
	v_add_f32_e32 v134, v134, v135
	v_add_f32_e32 v136, 0, v134
	s_waitcnt vmcnt(2)
	v_add_f32_e32 v134, v229, v228
	v_add_f32_e32 v135, v230, v231
	v_add_f32_e32 v134, v134, v135
	v_add_f32_e32 v136, v136, v134
	s_waitcnt vmcnt(1)
	v_add_f32_e32 v134, v233, v232
	v_add_f32_e32 v135, v234, v235
	v_add_f32_e32 v134, v134, v135
	v_add_f32_e32 v136, v136, v134
	s_waitcnt vmcnt(0)
	v_add_f32_e32 v134, v237, v236
	v_add_f32_e32 v135, v238, v239
	v_add_f32_e32 v134, v134, v135
	v_add_f32_e32 v128, v136, v134
	s_nop 0
	v_fmamk_f32 v128, v128, 0x3a800000, v185
	v_rsq_f32_e32 v128, v128
	ds_write_b32 v204, v128

; #define LAS __attribute__((address_space(3)))
; __device__ __forceinline__ void panel_rs_fill(const float* rowss, int pm, LAS float* rs_lds, int tid) {
;     if (tid < 256) {
;         const float* p = rowss + (size_t)(pm * 256 + tid) * 16; float sacc = 0.f;
; #pragma unroll
;         for (int q = 0; q < 4; ++q) { const f32x4 a = *(const f32x4*)(p + 4 * q); sacc += (a[0] + a[1]) + (a[2] + a[3]); asm volatile("" : "+v"(sacc)); }
;         rs_lds[tid] = __builtin_amdgcn_rsqf(sacc * (1.f / 1024.f) + EPS);
;     }
;     __device__ __forceinline__ void operator()(const f32x4 (&acc)[2][2][4][2], const Unit& u, int wr, int wc, int fr, int fq) const {
;     ...
;         if (((volatile LAS int*)rs_lds)[256] != u.pm) panel_rs_fill(rowss, u.pm, rs_lds, (wr * 4 + wc) * 64 + fq * 16 + fr);
.LBB0_413:
	s_and_b64 vcc, exec, s[10:11]
	s_cbranch_vccz .LBB0_421
	v_readlane_b32 s4, v226, 41
	s_nop 1
	v_mov_b32_e32 v128, s4
	ds_read_b32 v128, v128 offset:1024
	s_waitcnt lgkmcnt(0)
	v_cmp_eq_u32_e32 vcc, s94, v128
	s_cbranch_vccnz .LBB0_420
	s_mov_b64 s[10:11], exec
	v_readlane_b32 s4, v226, 35
	v_readlane_b32 s5, v226, 36
	s_and_b64 s[4:5], s[10:11], s[4:5]
	s_mov_b64 exec, s[4:5]
	s_cbranch_execz .LBB0_417
	v_add_u32_e32 v128, s40, v201
	v_ashrrev_i32_e32 v129, 31, v128
	v_readlane_b32 s4, v226, 42
	v_lshlrev_b64 v[128:129], 6, v[128:129]
	v_readlane_b32 s5, v226, 43
	s_nop 1
	v_lshl_add_u64 v[132:133], s[4:5], 0, v[128:129]
	global_load_dwordx4 v[128:131], v[132:133], off
	global_load_dwordx4 v[228:231], v[132:133], off offset:16
	global_load_dwordx4 v[232:235], v[132:133], off offset:32
	global_load_dwordx4 v[236:239], v[132:133], off offset:48
	s_waitcnt vmcnt(3)
	v_add_f32_e32 v134, v129, v128
	v_add_f32_e32 v135, v130, v131
	v_add_f32_e32 v134, v134, v135
	v_add_f32_e32 v136, 0, v134
	s_waitcnt vmcnt(2)
	v_add_f32_e32 v134, v229, v228
	v_add_f32_e32 v135, v230, v231
	v_add_f32_e32 v134, v134, v135
	v_add_f32_e32 v136, v136, v134
	s_waitcnt vmcnt(1)
	v_add_f32_e32 v134, v233, v232
	v_add_f32_e32 v135, v234, v235
	v_add_f32_e32 v134, v134, v135
	v_add_f32_e32 v136, v136, v134
	s_waitcnt vmcnt(0)
	v_add_f32_e32 v134, v237, v236
	v_add_f32_e32 v135, v238, v239
	v_add_f32_e32 v134, v134, v135
	v_add_f32_e32 v128, v136, v134
	s_nop 0
	v_fmamk_f32 v128, v128, 0x3a800000, v185
	v_rsq_f32_e32 v128, v128
	ds_write_b32 v202, v128

; __global__ void __launch_bounds__(512, 2) fwd_megakernel(Params P) {
	.amdhsa_kernel _Z14fwd_megakernel6Params
		.amdhsa_group_segment_fixed_size 0
		.amdhsa_private_segment_fixed_size 0
		.amdhsa_kernarg_size 464
		.amdhsa_user_sgpr_count 2
		.amdhsa_user_sgpr_dispatch_ptr 0
		.amdhsa_user_sgpr_queue_ptr 0
		.amdhsa_user_sgpr_kernarg_segment_ptr 1
		.amdhsa_user_sgpr_dispatch_id 0
		.amdhsa_user_sgpr_kernarg_preload_length 0
		.amdhsa_user_sgpr_kernarg_preload_offset 0
		.amdhsa_user_sgpr_private_segment_size 0
		.amdhsa_uses_dynamic_stack 0
		.amdhsa_enable_private_segment 0
		.amdhsa_system_sgpr_workgroup_id_x 1
		.amdhsa_system_sgpr_workgroup_id_y 0
		.amdhsa_system_sgpr_workgroup_id_z 0
		.amdhsa_system_sgpr_workgroup_info 0
		.amdhsa_system_vgpr_workitem_id 2
		.amdhsa_next_free_vgpr 240
		.amdhsa_next_free_sgpr 100
		.amdhsa_accum_offset 240
		.amdhsa_reserve_vcc 1
		.amdhsa_float_round_mode_32 0
		.amdhsa_float_round_mode_16_64 0
		.amdhsa_float_denorm_mode_32 3
		.amdhsa_float_denorm_mode_16_64 3
		.amdhsa_dx10_clamp 1
		.amdhsa_ieee_mode 1
		.amdhsa_fp16_overflow 0
		.amdhsa_tg_split 0
		.amdhsa_exception_fp_ieee_invalid_op 0
		.amdhsa_exception_fp_denorm_src 0
		.amdhsa_exception_fp_ieee_div_zero 0
		.amdhsa_exception_fp_ieee_overflow 0
		.amdhsa_exception_fp_ieee_underflow 0
		.amdhsa_exception_fp_ieee_inexact 0
		.amdhsa_exception_int_div_zero 0
	.end_amdhsa_kernel

; __global__ void __launch_bounds__(512, 2) fwd_megakernel(Params P) {
amdhsa.kernels:
  - .agpr_count:     0
    .args:
      - .offset:         0
        .size:           208
        .value_kind:     by_value
      - .offset:         208
        .size:           4
        .value_kind:     hidden_block_count_x
      - .offset:         212
        .size:           4
        .value_kind:     hidden_block_count_y
      - .offset:         216
        .size:           4
        .value_kind:     hidden_block_count_z
      - .offset:         220
        .size:           2
        .value_kind:     hidden_group_size_x
      - .offset:         222
        .size:           2
        .value_kind:     hidden_group_size_y
      - .offset:         224
        .size:           2
        .value_kind:     hidden_group_size_z
      - .offset:         226
        .size:           2
        .value_kind:     hidden_remainder_x
      - .offset:         228
        .size:           2
        .value_kind:     hidden_remainder_y
      - .offset:         230
        .size:           2
        .value_kind:     hidden_remainder_z
      - .offset:         248
        .size:           8
        .value_kind:     hidden_global_offset_x
      - .offset:         256
        .size:           8
        .value_kind:     hidden_global_offset_y
      - .offset:         264
        .size:           8
        .value_kind:     hidden_global_offset_z
      - .offset:         272
        .size:           2
        .value_kind:     hidden_grid_dims
      - .offset:         296
        .size:           8
        .value_kind:     hidden_multigrid_sync_arg
      - .offset:         328
        .size:           4
        .value_kind:     hidden_dynamic_lds_size
    .group_segment_fixed_size: 0
    .kernarg_segment_align: 8
    .kernarg_segment_size: 464
    .language:       OpenCL C
    .language_version:
      - 2
      - 0
    .max_flat_workgroup_size: 512
    .name:           _Z14fwd_megakernel6Params
    .private_segment_fixed_size: 0
    .sgpr_count:     106
    .sgpr_spill_count: 165
    .symbol:         _Z14fwd_megakernel6Params.kd
    .uniform_work_group_size: 1
    .uses_dynamic_stack: false
    .vgpr_count:     240
    .vgpr_spill_count: 0
    .wavefront_size: 64
